# hand-written EpiUq epilogue: loads batched up front, paired permlane32_swap rope, packed scale pass
# baseline (speedup 1.0000x reference)
.LBB0_271:
	s_lshl_b32 s0, s29, 8
	s_add_i32 s0, s0, s82
	v_and_or_b32 v0, v193, 15, s0
	v_bfe_u32 v218, v193, 4, 2
	v_lshlrev_b32_e32 v219, 4, v218
	v_mad_u32_u24 v252, v0, s61, v219
	v_add_u32_e32 v253, 0x1200, v252
	v_add_u32_e32 v254, 0x3000, v252
	v_add_u32_e32 v255, 0x4200, v252
	global_load_dwordx4 v[150:153], v252, s[16:17]
	global_load_dwordx4 v[154:157], v252, s[16:17] offset:1536
	global_load_dwordx4 v[158:161], v252, s[16:17] offset:3072
	global_load_dwordx4 v[162:165], v253, s[16:17]
	global_load_dwordx4 v[166:169], v254, s[16:17]
	global_load_dwordx4 v[170:173], v254, s[16:17] offset:1536
	global_load_dwordx4 v[174:177], v254, s[16:17] offset:3072
	global_load_dwordx4 v[180:183], v255, s[16:17]
	s_lshl_b32 s0, s28, 3
	s_or_b32 s0, s0, s81
	s_mul_i32 s2, s0, 43
	s_lshr_b32 s2, s2, 7
	s_mul_i32 s2, s2, 3
	s_sub_i32 s0, s0, s2
	s_lshl_b32 s2, s28, 9
	s_lshl_b32 s24, s83, 1
	s_or_b32 s2, s2, s24
	v_lshl_or_b32 v219, v218, 4, s2
	v_mad_u32_u24 v219, v0, s47, v219
	s_mov_b32 vcc_lo, -1
	s_mov_b32 vcc_hi, 0xffff
	s_cmp_eq_u32 s0, 2
	s_cbranch_scc1 .Luq_r0
	s_cmp_eq_u32 s0, 1
	s_cbranch_scc1 .Luq_r1
	s_waitcnt vmcnt(0)
	v_add_f32_e32 v150, v151, v150
	v_add_f32_e32 v152, v152, v153
	v_add_f32_e32 v154, v155, v154
	v_add_f32_e32 v156, v156, v157
	v_add_f32_e32 v158, v159, v158
	v_add_f32_e32 v160, v160, v161
	v_add_f32_e32 v162, v163, v162
	v_add_f32_e32 v164, v164, v165
	v_add_f32_e32 v166, v167, v166
	v_add_f32_e32 v168, v168, v169
	v_add_f32_e32 v170, v171, v170
	v_add_f32_e32 v172, v172, v173
	v_add_f32_e32 v174, v175, v174
	v_add_f32_e32 v176, v176, v177
	v_add_f32_e32 v180, v181, v180
	v_add_f32_e32 v182, v182, v183
	v_add_f32_e32 v150, v150, v152
	v_add_f32_e32 v154, v154, v156
	v_add_f32_e32 v158, v158, v160
	v_add_f32_e32 v162, v162, v164
	v_add_f32_e32 v166, v166, v168
	v_add_f32_e32 v170, v170, v172
	v_add_f32_e32 v174, v174, v176
	v_add_f32_e32 v180, v180, v182
	v_cndmask_b32_e32 v150, 0, v150, vcc
	v_cndmask_b32_e32 v154, 0, v154, vcc
	v_cndmask_b32_e32 v158, 0, v158, vcc
	v_cndmask_b32_e32 v162, 0, v162, vcc
	v_cndmask_b32_e32 v166, 0, v166, vcc
	v_cndmask_b32_e32 v170, 0, v170, vcc
	v_cndmask_b32_e32 v174, 0, v174, vcc
	v_cndmask_b32_e32 v180, 0, v180, vcc
	ds_swizzle_b32 v151, v150 offset:swizzle(SWAP,16)
	ds_swizzle_b32 v155, v154 offset:swizzle(SWAP,16)
	ds_swizzle_b32 v159, v158 offset:swizzle(SWAP,16)
	ds_swizzle_b32 v163, v162 offset:swizzle(SWAP,16)
	ds_swizzle_b32 v167, v166 offset:swizzle(SWAP,16)
	ds_swizzle_b32 v171, v170 offset:swizzle(SWAP,16)
	ds_swizzle_b32 v175, v174 offset:swizzle(SWAP,16)
	ds_swizzle_b32 v181, v180 offset:swizzle(SWAP,16)
	s_waitcnt lgkmcnt(0)
	v_add_f32_e32 v150, v150, v151
	v_add_f32_e32 v154, v154, v155
	v_add_f32_e32 v158, v158, v159
	v_add_f32_e32 v162, v162, v163
	v_add_f32_e32 v166, v166, v167
	v_add_f32_e32 v170, v170, v171
	v_add_f32_e32 v174, v174, v175
	v_add_f32_e32 v180, v180, v181
	v_mov_b32_e32 v152, v150
	v_mov_b32_e32 v156, v154
	v_mov_b32_e32 v160, v158
	v_mov_b32_e32 v164, v162
	v_mov_b32_e32 v168, v166
	v_mov_b32_e32 v172, v170
	v_mov_b32_e32 v176, v174
	v_mov_b32_e32 v182, v180
	v_permlane32_swap_b32_e32 v150, v152
	v_permlane32_swap_b32_e32 v154, v156
	v_permlane32_swap_b32_e32 v158, v160
	v_permlane32_swap_b32_e32 v162, v164
	v_permlane32_swap_b32_e32 v166, v168
	v_permlane32_swap_b32_e32 v170, v172
	v_permlane32_swap_b32_e32 v174, v176
	v_permlane32_swap_b32_e32 v180, v182
	v_add_f32_e32 v150, v150, v152
	v_add_f32_e32 v154, v154, v156
	v_add_f32_e32 v158, v158, v160
	v_add_f32_e32 v162, v162, v164
	v_add_f32_e32 v166, v166, v168
	v_add_f32_e32 v170, v170, v172
	v_add_f32_e32 v174, v174, v176
	v_add_f32_e32 v180, v180, v182
	v_fmamk_f32 v150, v150, 0x3b2aaaab, v192
	v_fmamk_f32 v154, v154, 0x3b2aaaab, v192
	v_fmamk_f32 v158, v158, 0x3b2aaaab, v192
	v_fmamk_f32 v162, v162, 0x3b2aaaab, v192
	v_fmamk_f32 v166, v166, 0x3b2aaaab, v192
	v_fmamk_f32 v170, v170, 0x3b2aaaab, v192
	v_fmamk_f32 v174, v174, 0x3b2aaaab, v192
	v_fmamk_f32 v180, v180, 0x3b2aaaab, v192
	v_rsq_f32_e32 v150, v150
	v_rsq_f32_e32 v154, v154
	v_rsq_f32_e32 v158, v158
	v_rsq_f32_e32 v162, v162
	v_rsq_f32_e32 v166, v166
	v_rsq_f32_e32 v170, v170
	v_rsq_f32_e32 v174, v174
	v_rsq_f32_e32 v180, v180
	v_mul_f32_e32 v150, 0x3e16c740, v150
	v_mul_f32_e32 v154, 0x3e16c740, v154
	v_mul_f32_e32 v158, 0x3e16c740, v158
	v_mul_f32_e32 v162, 0x3e16c740, v162
	v_mul_f32_e32 v166, 0x3e16c740, v166
	v_mul_f32_e32 v170, 0x3e16c740, v170
	v_mul_f32_e32 v174, 0x3e16c740, v174
	v_mul_f32_e32 v180, 0x3e16c740, v180
	v_pk_mul_f32 v[134:135], v[134:135], v[150:151] op_sel_hi:[1,0]
	v_pk_mul_f32 v[136:137], v[136:137], v[150:151] op_sel_hi:[1,0]
	v_pk_mul_f32 v[130:131], v[130:131], v[150:151] op_sel_hi:[1,0]
	v_pk_mul_f32 v[132:133], v[132:133], v[150:151] op_sel_hi:[1,0]
	v_pk_mul_f32 v[126:127], v[126:127], v[150:151] op_sel_hi:[1,0]
	v_pk_mul_f32 v[128:129], v[128:129], v[150:151] op_sel_hi:[1,0]
	v_pk_mul_f32 v[122:123], v[122:123], v[150:151] op_sel_hi:[1,0]
	v_pk_mul_f32 v[124:125], v[124:125], v[150:151] op_sel_hi:[1,0]
	v_pk_mul_f32 v[118:119], v[118:119], v[154:155] op_sel_hi:[1,0]
	v_pk_mul_f32 v[120:121], v[120:121], v[154:155] op_sel_hi:[1,0]
	v_pk_mul_f32 v[114:115], v[114:115], v[154:155] op_sel_hi:[1,0]
	v_pk_mul_f32 v[116:117], v[116:117], v[154:155] op_sel_hi:[1,0]
	v_pk_mul_f32 v[110:111], v[110:111], v[154:155] op_sel_hi:[1,0]
	v_pk_mul_f32 v[112:113], v[112:113], v[154:155] op_sel_hi:[1,0]
	v_pk_mul_f32 v[106:107], v[106:107], v[154:155] op_sel_hi:[1,0]
	v_pk_mul_f32 v[108:109], v[108:109], v[154:155] op_sel_hi:[1,0]
	v_pk_mul_f32 v[102:103], v[102:103], v[158:159] op_sel_hi:[1,0]
	v_pk_mul_f32 v[104:105], v[104:105], v[158:159] op_sel_hi:[1,0]
	v_pk_mul_f32 v[98:99], v[98:99], v[158:159] op_sel_hi:[1,0]
	v_pk_mul_f32 v[100:101], v[100:101], v[158:159] op_sel_hi:[1,0]
	v_pk_mul_f32 v[94:95], v[94:95], v[158:159] op_sel_hi:[1,0]
	v_pk_mul_f32 v[96:97], v[96:97], v[158:159] op_sel_hi:[1,0]
	v_pk_mul_f32 v[90:91], v[90:91], v[158:159] op_sel_hi:[1,0]
	v_pk_mul_f32 v[92:93], v[92:93], v[158:159] op_sel_hi:[1,0]
	v_pk_mul_f32 v[86:87], v[86:87], v[162:163] op_sel_hi:[1,0]
	v_pk_mul_f32 v[88:89], v[88:89], v[162:163] op_sel_hi:[1,0]
	v_pk_mul_f32 v[82:83], v[82:83], v[162:163] op_sel_hi:[1,0]
	v_pk_mul_f32 v[84:85], v[84:85], v[162:163] op_sel_hi:[1,0]
	v_pk_mul_f32 v[78:79], v[78:79], v[162:163] op_sel_hi:[1,0]
	v_pk_mul_f32 v[80:81], v[80:81], v[162:163] op_sel_hi:[1,0]
	v_pk_mul_f32 v[74:75], v[74:75], v[162:163] op_sel_hi:[1,0]
	v_pk_mul_f32 v[76:77], v[76:77], v[162:163] op_sel_hi:[1,0]
	v_pk_mul_f32 v[70:71], v[70:71], v[166:167] op_sel_hi:[1,0]
	v_pk_mul_f32 v[72:73], v[72:73], v[166:167] op_sel_hi:[1,0]
	v_pk_mul_f32 v[66:67], v[66:67], v[166:167] op_sel_hi:[1,0]
	v_pk_mul_f32 v[68:69], v[68:69], v[166:167] op_sel_hi:[1,0]
	v_pk_mul_f32 v[62:63], v[62:63], v[166:167] op_sel_hi:[1,0]
	v_pk_mul_f32 v[64:65], v[64:65], v[166:167] op_sel_hi:[1,0]
	v_pk_mul_f32 v[58:59], v[58:59], v[166:167] op_sel_hi:[1,0]
	v_pk_mul_f32 v[60:61], v[60:61], v[166:167] op_sel_hi:[1,0]
	v_pk_mul_f32 v[46:47], v[46:47], v[170:171] op_sel_hi:[1,0]
	v_pk_mul_f32 v[48:49], v[48:49], v[170:171] op_sel_hi:[1,0]
	v_pk_mul_f32 v[42:43], v[42:43], v[170:171] op_sel_hi:[1,0]
	v_pk_mul_f32 v[44:45], v[44:45], v[170:171] op_sel_hi:[1,0]
	v_pk_mul_f32 v[38:39], v[38:39], v[170:171] op_sel_hi:[1,0]
	v_pk_mul_f32 v[40:41], v[40:41], v[170:171] op_sel_hi:[1,0]
	v_pk_mul_f32 v[34:35], v[34:35], v[170:171] op_sel_hi:[1,0]
	v_pk_mul_f32 v[36:37], v[36:37], v[170:171] op_sel_hi:[1,0]
	v_pk_mul_f32 v[30:31], v[30:31], v[174:175] op_sel_hi:[1,0]
	v_pk_mul_f32 v[32:33], v[32:33], v[174:175] op_sel_hi:[1,0]
	v_pk_mul_f32 v[26:27], v[26:27], v[174:175] op_sel_hi:[1,0]
	v_pk_mul_f32 v[28:29], v[28:29], v[174:175] op_sel_hi:[1,0]
	v_pk_mul_f32 v[22:23], v[22:23], v[174:175] op_sel_hi:[1,0]
	v_pk_mul_f32 v[24:25], v[24:25], v[174:175] op_sel_hi:[1,0]
	v_pk_mul_f32 v[18:19], v[18:19], v[174:175] op_sel_hi:[1,0]
	v_pk_mul_f32 v[20:21], v[20:21], v[174:175] op_sel_hi:[1,0]
	v_pk_mul_f32 v[14:15], v[14:15], v[180:181] op_sel_hi:[1,0]
	v_pk_mul_f32 v[16:17], v[16:17], v[180:181] op_sel_hi:[1,0]
	v_pk_mul_f32 v[10:11], v[10:11], v[180:181] op_sel_hi:[1,0]
	v_pk_mul_f32 v[12:13], v[12:13], v[180:181] op_sel_hi:[1,0]
	v_pk_mul_f32 v[6:7], v[6:7], v[180:181] op_sel_hi:[1,0]
	v_pk_mul_f32 v[8:9], v[8:9], v[180:181] op_sel_hi:[1,0]
	v_pk_mul_f32 v[2:3], v[2:3], v[180:181] op_sel_hi:[1,0]
	v_pk_mul_f32 v[4:5], v[4:5], v[180:181] op_sel_hi:[1,0]
	v_cvt_pk_bf16_f32 v134, v134, v135
	v_cvt_pk_bf16_f32 v135, v136, v137
	v_cvt_pk_bf16_f32 v136, v130, v131
	v_cvt_pk_bf16_f32 v137, v132, v133
	v_add_u32_e32 v252, 0x0, v219
	global_store_dwordx4 v252, v[134:137], s[8:9]
	v_cvt_pk_bf16_f32 v126, v126, v127
	v_cvt_pk_bf16_f32 v127, v128, v129
	v_cvt_pk_bf16_f32 v128, v122, v123
	v_cvt_pk_bf16_f32 v129, v124, v125
	v_add_u32_e32 v253, 0x0, v219
	global_store_dwordx4 v253, v[126:129], s[8:9] offset:256
	v_cvt_pk_bf16_f32 v118, v118, v119
	v_cvt_pk_bf16_f32 v119, v120, v121
	v_cvt_pk_bf16_f32 v120, v114, v115
	v_cvt_pk_bf16_f32 v121, v116, v117
	v_add_u32_e32 v252, 0xc000, v219
	global_store_dwordx4 v252, v[118:121], s[8:9]
	v_cvt_pk_bf16_f32 v110, v110, v111
	v_cvt_pk_bf16_f32 v111, v112, v113
	v_cvt_pk_bf16_f32 v112, v106, v107
	v_cvt_pk_bf16_f32 v113, v108, v109
	v_add_u32_e32 v253, 0xc000, v219
	global_store_dwordx4 v253, v[110:113], s[8:9] offset:256
	v_cvt_pk_bf16_f32 v102, v102, v103
	v_cvt_pk_bf16_f32 v103, v104, v105
	v_cvt_pk_bf16_f32 v104, v98, v99
	v_cvt_pk_bf16_f32 v105, v100, v101
	v_add_u32_e32 v252, 0x18000, v219
	global_store_dwordx4 v252, v[102:105], s[8:9]
	v_cvt_pk_bf16_f32 v94, v94, v95
	v_cvt_pk_bf16_f32 v95, v96, v97
	v_cvt_pk_bf16_f32 v96, v90, v91
	v_cvt_pk_bf16_f32 v97, v92, v93
	v_add_u32_e32 v253, 0x18000, v219
	global_store_dwordx4 v253, v[94:97], s[8:9] offset:256
	v_cvt_pk_bf16_f32 v86, v86, v87
	v_cvt_pk_bf16_f32 v87, v88, v89
	v_cvt_pk_bf16_f32 v88, v82, v83
	v_cvt_pk_bf16_f32 v89, v84, v85
	v_add_u32_e32 v252, 0x24000, v219
	global_store_dwordx4 v252, v[86:89], s[8:9]
	v_cvt_pk_bf16_f32 v78, v78, v79
	v_cvt_pk_bf16_f32 v79, v80, v81
	v_cvt_pk_bf16_f32 v80, v74, v75
	v_cvt_pk_bf16_f32 v81, v76, v77
	v_add_u32_e32 v253, 0x24000, v219
	global_store_dwordx4 v253, v[78:81], s[8:9] offset:256
	v_cvt_pk_bf16_f32 v70, v70, v71
	v_cvt_pk_bf16_f32 v71, v72, v73
	v_cvt_pk_bf16_f32 v72, v66, v67
	v_cvt_pk_bf16_f32 v73, v68, v69
	v_add_u32_e32 v252, 0x60000, v219
	global_store_dwordx4 v252, v[70:73], s[8:9]
	v_cvt_pk_bf16_f32 v62, v62, v63
	v_cvt_pk_bf16_f32 v63, v64, v65
	v_cvt_pk_bf16_f32 v64, v58, v59
	v_cvt_pk_bf16_f32 v65, v60, v61
	v_add_u32_e32 v253, 0x60000, v219
	global_store_dwordx4 v253, v[62:65], s[8:9] offset:256
	v_cvt_pk_bf16_f32 v46, v46, v47
	v_cvt_pk_bf16_f32 v47, v48, v49
	v_cvt_pk_bf16_f32 v48, v42, v43
	v_cvt_pk_bf16_f32 v49, v44, v45
	v_add_u32_e32 v252, 0x6c000, v219
	global_store_dwordx4 v252, v[46:49], s[8:9]
	v_cvt_pk_bf16_f32 v38, v38, v39
	v_cvt_pk_bf16_f32 v39, v40, v41
	v_cvt_pk_bf16_f32 v40, v34, v35
	v_cvt_pk_bf16_f32 v41, v36, v37
	v_add_u32_e32 v253, 0x6c000, v219
	global_store_dwordx4 v253, v[38:41], s[8:9] offset:256
	v_cvt_pk_bf16_f32 v30, v30, v31
	v_cvt_pk_bf16_f32 v31, v32, v33
	v_cvt_pk_bf16_f32 v32, v26, v27
	v_cvt_pk_bf16_f32 v33, v28, v29
	v_add_u32_e32 v252, 0x78000, v219
	global_store_dwordx4 v252, v[30:33], s[8:9]
	v_cvt_pk_bf16_f32 v22, v22, v23
	v_cvt_pk_bf16_f32 v23, v24, v25
	v_cvt_pk_bf16_f32 v24, v18, v19
	v_cvt_pk_bf16_f32 v25, v20, v21
	v_add_u32_e32 v253, 0x78000, v219
	global_store_dwordx4 v253, v[22:25], s[8:9] offset:256
	v_cvt_pk_bf16_f32 v14, v14, v15
	v_cvt_pk_bf16_f32 v15, v16, v17
	v_cvt_pk_bf16_f32 v16, v10, v11
	v_cvt_pk_bf16_f32 v17, v12, v13
	v_add_u32_e32 v252, 0x84000, v219
	global_store_dwordx4 v252, v[14:17], s[8:9]
	v_cvt_pk_bf16_f32 v6, v6, v7
	v_cvt_pk_bf16_f32 v7, v8, v9
	v_cvt_pk_bf16_f32 v8, v2, v3
	v_cvt_pk_bf16_f32 v9, v4, v5
	v_add_u32_e32 v253, 0x84000, v219
	global_store_dwordx4 v253, v[6:9], s[8:9] offset:256
	s_branch .Luq_end
.Luq_r0:
	v_and_b32_e32 v252, 1, v218
	v_and_b32_e32 v253, 2, v218
	v_lshlrev_b32_e32 v254, 6, v0
	v_lshl_add_u32 v254, v252, 5, v254
	v_lshl_add_u32 v254, v253, 3, v254
	v_add_u32_e32 v255, 0x2000, v254
	global_load_dwordx4 v[228:231], v254, s[10:11]
	global_load_dwordx4 v[232:235], v254, s[12:13]
	global_load_dwordx4 v[236:239], v254, s[10:11] offset:1024
	global_load_dwordx4 v[50:53], v254, s[12:13] offset:1024
	global_load_dwordx4 v[54:57], v254, s[10:11] offset:2048
	global_load_dwordx4 v[184:187], v254, s[12:13] offset:2048
	global_load_dwordx4 v[188:191], v254, s[10:11] offset:3072
	global_load_dwordx4 v[214:217], v254, s[12:13] offset:3072
	s_waitcnt vmcnt(8)
	v_add_f32_e32 v150, v151, v150
	v_add_f32_e32 v152, v152, v153
	v_add_f32_e32 v154, v155, v154
	v_add_f32_e32 v156, v156, v157
	v_add_f32_e32 v158, v159, v158
	v_add_f32_e32 v160, v160, v161
	v_add_f32_e32 v162, v163, v162
	v_add_f32_e32 v164, v164, v165
	v_add_f32_e32 v166, v167, v166
	v_add_f32_e32 v168, v168, v169
	v_add_f32_e32 v170, v171, v170
	v_add_f32_e32 v172, v172, v173
	v_add_f32_e32 v174, v175, v174
	v_add_f32_e32 v176, v176, v177
	v_add_f32_e32 v180, v181, v180
	v_add_f32_e32 v182, v182, v183
	v_add_f32_e32 v150, v150, v152
	v_add_f32_e32 v154, v154, v156
	v_add_f32_e32 v158, v158, v160
	v_add_f32_e32 v162, v162, v164
	v_add_f32_e32 v166, v166, v168
	v_add_f32_e32 v170, v170, v172
	v_add_f32_e32 v174, v174, v176
	v_add_f32_e32 v180, v180, v182
	v_cndmask_b32_e32 v150, 0, v150, vcc
	v_cndmask_b32_e32 v154, 0, v154, vcc
	v_cndmask_b32_e32 v158, 0, v158, vcc
	v_cndmask_b32_e32 v162, 0, v162, vcc
	v_cndmask_b32_e32 v166, 0, v166, vcc
	v_cndmask_b32_e32 v170, 0, v170, vcc
	v_cndmask_b32_e32 v174, 0, v174, vcc
	v_cndmask_b32_e32 v180, 0, v180, vcc
	ds_swizzle_b32 v151, v150 offset:swizzle(SWAP,16)
	ds_swizzle_b32 v155, v154 offset:swizzle(SWAP,16)
	ds_swizzle_b32 v159, v158 offset:swizzle(SWAP,16)
	ds_swizzle_b32 v163, v162 offset:swizzle(SWAP,16)
	ds_swizzle_b32 v167, v166 offset:swizzle(SWAP,16)
	ds_swizzle_b32 v171, v170 offset:swizzle(SWAP,16)
	ds_swizzle_b32 v175, v174 offset:swizzle(SWAP,16)
	ds_swizzle_b32 v181, v180 offset:swizzle(SWAP,16)
	s_waitcnt lgkmcnt(0)
	v_add_f32_e32 v150, v150, v151
	v_add_f32_e32 v154, v154, v155
	v_add_f32_e32 v158, v158, v159
	v_add_f32_e32 v162, v162, v163
	v_add_f32_e32 v166, v166, v167
	v_add_f32_e32 v170, v170, v171
	v_add_f32_e32 v174, v174, v175
	v_add_f32_e32 v180, v180, v181
	v_mov_b32_e32 v152, v150
	v_mov_b32_e32 v156, v154
	v_mov_b32_e32 v160, v158
	v_mov_b32_e32 v164, v162
	v_mov_b32_e32 v168, v166
	v_mov_b32_e32 v172, v170
	v_mov_b32_e32 v176, v174
	v_mov_b32_e32 v182, v180
	v_permlane32_swap_b32_e32 v150, v152
	v_permlane32_swap_b32_e32 v154, v156
	v_permlane32_swap_b32_e32 v158, v160
	v_permlane32_swap_b32_e32 v162, v164
	v_permlane32_swap_b32_e32 v166, v168
	v_permlane32_swap_b32_e32 v170, v172
	v_permlane32_swap_b32_e32 v174, v176
	v_permlane32_swap_b32_e32 v180, v182
	v_add_f32_e32 v150, v150, v152
	v_add_f32_e32 v154, v154, v156
	v_add_f32_e32 v158, v158, v160
	v_add_f32_e32 v162, v162, v164
	v_add_f32_e32 v166, v166, v168
	v_add_f32_e32 v170, v170, v172
	v_add_f32_e32 v174, v174, v176
	v_add_f32_e32 v180, v180, v182
	v_fmamk_f32 v150, v150, 0x3b2aaaab, v192
	v_fmamk_f32 v154, v154, 0x3b2aaaab, v192
	v_fmamk_f32 v158, v158, 0x3b2aaaab, v192
	v_fmamk_f32 v162, v162, 0x3b2aaaab, v192
	v_fmamk_f32 v166, v166, 0x3b2aaaab, v192
	v_fmamk_f32 v170, v170, 0x3b2aaaab, v192
	v_fmamk_f32 v174, v174, 0x3b2aaaab, v192
	v_fmamk_f32 v180, v180, 0x3b2aaaab, v192
	v_rsq_f32_e32 v150, v150
	v_rsq_f32_e32 v154, v154
	v_rsq_f32_e32 v158, v158
	v_rsq_f32_e32 v162, v162
	v_rsq_f32_e32 v166, v166
	v_rsq_f32_e32 v170, v170
	v_rsq_f32_e32 v174, v174
	v_rsq_f32_e32 v180, v180
	v_mul_f32_e32 v150, 0x3e16c740, v150
	v_mul_f32_e32 v154, 0x3e16c740, v154
	v_mul_f32_e32 v158, 0x3e16c740, v158
	v_mul_f32_e32 v162, 0x3e16c740, v162
	v_mul_f32_e32 v166, 0x3e16c740, v166
	v_mul_f32_e32 v170, 0x3e16c740, v170
	v_mul_f32_e32 v174, 0x3e16c740, v174
	v_mul_f32_e32 v180, 0x3e16c740, v180
	v_pk_mul_f32 v[134:135], v[134:135], v[150:151] op_sel_hi:[1,0]
	v_pk_mul_f32 v[136:137], v[136:137], v[150:151] op_sel_hi:[1,0]
	v_pk_mul_f32 v[130:131], v[130:131], v[150:151] op_sel_hi:[1,0]
	v_pk_mul_f32 v[132:133], v[132:133], v[150:151] op_sel_hi:[1,0]
	v_pk_mul_f32 v[126:127], v[126:127], v[150:151] op_sel_hi:[1,0]
	v_pk_mul_f32 v[128:129], v[128:129], v[150:151] op_sel_hi:[1,0]
	v_pk_mul_f32 v[122:123], v[122:123], v[150:151] op_sel_hi:[1,0]
	v_pk_mul_f32 v[124:125], v[124:125], v[150:151] op_sel_hi:[1,0]
	v_pk_mul_f32 v[118:119], v[118:119], v[154:155] op_sel_hi:[1,0]
	v_pk_mul_f32 v[120:121], v[120:121], v[154:155] op_sel_hi:[1,0]
	v_pk_mul_f32 v[114:115], v[114:115], v[154:155] op_sel_hi:[1,0]
	v_pk_mul_f32 v[116:117], v[116:117], v[154:155] op_sel_hi:[1,0]
	v_pk_mul_f32 v[110:111], v[110:111], v[154:155] op_sel_hi:[1,0]
	v_pk_mul_f32 v[112:113], v[112:113], v[154:155] op_sel_hi:[1,0]
	v_pk_mul_f32 v[106:107], v[106:107], v[154:155] op_sel_hi:[1,0]
	v_pk_mul_f32 v[108:109], v[108:109], v[154:155] op_sel_hi:[1,0]
	v_pk_mul_f32 v[102:103], v[102:103], v[158:159] op_sel_hi:[1,0]
	v_pk_mul_f32 v[104:105], v[104:105], v[158:159] op_sel_hi:[1,0]
	v_pk_mul_f32 v[98:99], v[98:99], v[158:159] op_sel_hi:[1,0]
	v_pk_mul_f32 v[100:101], v[100:101], v[158:159] op_sel_hi:[1,0]
	v_pk_mul_f32 v[94:95], v[94:95], v[158:159] op_sel_hi:[1,0]
	v_pk_mul_f32 v[96:97], v[96:97], v[158:159] op_sel_hi:[1,0]
	v_pk_mul_f32 v[90:91], v[90:91], v[158:159] op_sel_hi:[1,0]
	v_pk_mul_f32 v[92:93], v[92:93], v[158:159] op_sel_hi:[1,0]
	v_pk_mul_f32 v[86:87], v[86:87], v[162:163] op_sel_hi:[1,0]
	v_pk_mul_f32 v[88:89], v[88:89], v[162:163] op_sel_hi:[1,0]
	v_pk_mul_f32 v[82:83], v[82:83], v[162:163] op_sel_hi:[1,0]
	v_pk_mul_f32 v[84:85], v[84:85], v[162:163] op_sel_hi:[1,0]
	v_pk_mul_f32 v[78:79], v[78:79], v[162:163] op_sel_hi:[1,0]
	v_pk_mul_f32 v[80:81], v[80:81], v[162:163] op_sel_hi:[1,0]
	v_pk_mul_f32 v[74:75], v[74:75], v[162:163] op_sel_hi:[1,0]
	v_pk_mul_f32 v[76:77], v[76:77], v[162:163] op_sel_hi:[1,0]
	v_pk_mul_f32 v[70:71], v[70:71], v[166:167] op_sel_hi:[1,0]
	v_pk_mul_f32 v[72:73], v[72:73], v[166:167] op_sel_hi:[1,0]
	v_pk_mul_f32 v[66:67], v[66:67], v[166:167] op_sel_hi:[1,0]
	v_pk_mul_f32 v[68:69], v[68:69], v[166:167] op_sel_hi:[1,0]
	v_pk_mul_f32 v[62:63], v[62:63], v[166:167] op_sel_hi:[1,0]
	v_pk_mul_f32 v[64:65], v[64:65], v[166:167] op_sel_hi:[1,0]
	v_pk_mul_f32 v[58:59], v[58:59], v[166:167] op_sel_hi:[1,0]
	v_pk_mul_f32 v[60:61], v[60:61], v[166:167] op_sel_hi:[1,0]
	v_pk_mul_f32 v[46:47], v[46:47], v[170:171] op_sel_hi:[1,0]
	v_pk_mul_f32 v[48:49], v[48:49], v[170:171] op_sel_hi:[1,0]
	v_pk_mul_f32 v[42:43], v[42:43], v[170:171] op_sel_hi:[1,0]
	v_pk_mul_f32 v[44:45], v[44:45], v[170:171] op_sel_hi:[1,0]
	v_pk_mul_f32 v[38:39], v[38:39], v[170:171] op_sel_hi:[1,0]
	v_pk_mul_f32 v[40:41], v[40:41], v[170:171] op_sel_hi:[1,0]
	v_pk_mul_f32 v[34:35], v[34:35], v[170:171] op_sel_hi:[1,0]
	v_pk_mul_f32 v[36:37], v[36:37], v[170:171] op_sel_hi:[1,0]
	v_pk_mul_f32 v[30:31], v[30:31], v[174:175] op_sel_hi:[1,0]
	v_pk_mul_f32 v[32:33], v[32:33], v[174:175] op_sel_hi:[1,0]
	v_pk_mul_f32 v[26:27], v[26:27], v[174:175] op_sel_hi:[1,0]
	v_pk_mul_f32 v[28:29], v[28:29], v[174:175] op_sel_hi:[1,0]
	v_pk_mul_f32 v[22:23], v[22:23], v[174:175] op_sel_hi:[1,0]
	v_pk_mul_f32 v[24:25], v[24:25], v[174:175] op_sel_hi:[1,0]
	v_pk_mul_f32 v[18:19], v[18:19], v[174:175] op_sel_hi:[1,0]
	v_pk_mul_f32 v[20:21], v[20:21], v[174:175] op_sel_hi:[1,0]
	v_pk_mul_f32 v[14:15], v[14:15], v[180:181] op_sel_hi:[1,0]
	v_pk_mul_f32 v[16:17], v[16:17], v[180:181] op_sel_hi:[1,0]
	v_pk_mul_f32 v[10:11], v[10:11], v[180:181] op_sel_hi:[1,0]
	v_pk_mul_f32 v[12:13], v[12:13], v[180:181] op_sel_hi:[1,0]
	v_pk_mul_f32 v[6:7], v[6:7], v[180:181] op_sel_hi:[1,0]
	v_pk_mul_f32 v[8:9], v[8:9], v[180:181] op_sel_hi:[1,0]
	v_pk_mul_f32 v[2:3], v[2:3], v[180:181] op_sel_hi:[1,0]
	v_pk_mul_f32 v[4:5], v[4:5], v[180:181] op_sel_hi:[1,0]
	global_load_dwordx4 v[150:153], v255, s[10:11]
	global_load_dwordx4 v[154:157], v255, s[12:13]
	global_load_dwordx4 v[158:161], v255, s[10:11] offset:1024
	global_load_dwordx4 v[162:165], v255, s[12:13] offset:1024
	global_load_dwordx4 v[166:169], v255, s[10:11] offset:2048
	global_load_dwordx4 v[170:173], v255, s[12:13] offset:2048
	global_load_dwordx4 v[174:177], v255, s[10:11] offset:3072
	global_load_dwordx4 v[180:183], v255, s[12:13] offset:3072
	v_cvt_pk_bf16_f32 v126, v126, v127
	v_cvt_pk_bf16_f32 v127, v128, v129
	v_cvt_pk_bf16_f32 v128, v122, v123
	v_cvt_pk_bf16_f32 v129, v124, v125
	v_add_u32_e32 v252, 0x0, v219
	global_store_dwordx4 v252, v[126:129], s[8:9] offset:256
	v_cvt_pk_bf16_f32 v110, v110, v111
	v_cvt_pk_bf16_f32 v111, v112, v113
	v_cvt_pk_bf16_f32 v112, v106, v107
	v_cvt_pk_bf16_f32 v113, v108, v109
	v_add_u32_e32 v253, 0xc000, v219
	global_store_dwordx4 v253, v[110:113], s[8:9] offset:256
	v_cvt_pk_bf16_f32 v94, v94, v95
	v_cvt_pk_bf16_f32 v95, v96, v97
	v_cvt_pk_bf16_f32 v96, v90, v91
	v_cvt_pk_bf16_f32 v97, v92, v93
	v_add_u32_e32 v252, 0x18000, v219
	global_store_dwordx4 v252, v[94:97], s[8:9] offset:256
	v_cvt_pk_bf16_f32 v78, v78, v79
	v_cvt_pk_bf16_f32 v79, v80, v81
	v_cvt_pk_bf16_f32 v80, v74, v75
	v_cvt_pk_bf16_f32 v81, v76, v77
	v_add_u32_e32 v253, 0x24000, v219
	global_store_dwordx4 v253, v[78:81], s[8:9] offset:256
	v_cvt_pk_bf16_f32 v62, v62, v63
	v_cvt_pk_bf16_f32 v63, v64, v65
	v_cvt_pk_bf16_f32 v64, v58, v59
	v_cvt_pk_bf16_f32 v65, v60, v61
	v_add_u32_e32 v252, 0x60000, v219
	global_store_dwordx4 v252, v[62:65], s[8:9] offset:256
	v_cvt_pk_bf16_f32 v38, v38, v39
	v_cvt_pk_bf16_f32 v39, v40, v41
	v_cvt_pk_bf16_f32 v40, v34, v35
	v_cvt_pk_bf16_f32 v41, v36, v37
	v_add_u32_e32 v253, 0x6c000, v219
	global_store_dwordx4 v253, v[38:41], s[8:9] offset:256
	v_cvt_pk_bf16_f32 v22, v22, v23
	v_cvt_pk_bf16_f32 v23, v24, v25
	v_cvt_pk_bf16_f32 v24, v18, v19
	v_cvt_pk_bf16_f32 v25, v20, v21
	v_add_u32_e32 v252, 0x78000, v219
	global_store_dwordx4 v252, v[22:25], s[8:9] offset:256
	v_cvt_pk_bf16_f32 v6, v6, v7
	v_cvt_pk_bf16_f32 v7, v8, v9
	v_cvt_pk_bf16_f32 v8, v2, v3
	v_cvt_pk_bf16_f32 v9, v4, v5
	v_add_u32_e32 v253, 0x84000, v219
	global_store_dwordx4 v253, v[6:9], s[8:9] offset:256
	s_waitcnt vmcnt(20)
	v_permlane32_swap_b32_e32 v134, v130
	v_permlane32_swap_b32_e32 v135, v131
	v_permlane32_swap_b32_e32 v136, v132
	v_permlane32_swap_b32_e32 v137, v133
	v_permlane32_swap_b32_e32 v118, v114
	v_permlane32_swap_b32_e32 v119, v115
	v_permlane32_swap_b32_e32 v120, v116
	v_permlane32_swap_b32_e32 v121, v117
	v_pk_mul_f32 v[122:123], v[134:135], v[228:229]
	v_pk_mul_f32 v[124:125], v[136:137], v[230:231]
	v_pk_mul_f32 v[106:107], v[118:119], v[236:237]
	v_pk_mul_f32 v[108:109], v[120:121], v[238:239]
	v_pk_fma_f32 v[122:123], v[130:131], v[232:233], v[122:123] neg_lo:[1,0,0] neg_hi:[1,0,0]
	v_pk_fma_f32 v[124:125], v[132:133], v[234:235], v[124:125] neg_lo:[1,0,0] neg_hi:[1,0,0]
	v_pk_fma_f32 v[106:107], v[114:115], v[50:51], v[106:107] neg_lo:[1,0,0] neg_hi:[1,0,0]
	v_pk_fma_f32 v[108:109], v[116:117], v[52:53], v[108:109] neg_lo:[1,0,0] neg_hi:[1,0,0]
	v_pk_mul_f32 v[130:131], v[130:131], v[228:229]
	v_pk_mul_f32 v[132:133], v[132:133], v[230:231]
	v_pk_mul_f32 v[114:115], v[114:115], v[236:237]
	v_pk_mul_f32 v[116:117], v[116:117], v[238:239]
	v_pk_fma_f32 v[130:131], v[134:135], v[232:233], v[130:131]
	v_pk_fma_f32 v[132:133], v[136:137], v[234:235], v[132:133]
	v_pk_fma_f32 v[114:115], v[118:119], v[50:51], v[114:115]
	v_pk_fma_f32 v[116:117], v[120:121], v[52:53], v[116:117]
	v_permlane32_swap_b32_e32 v122, v130
	v_permlane32_swap_b32_e32 v123, v131
	v_permlane32_swap_b32_e32 v124, v132
	v_permlane32_swap_b32_e32 v125, v133
	v_permlane32_swap_b32_e32 v106, v114
	v_permlane32_swap_b32_e32 v107, v115
	v_permlane32_swap_b32_e32 v108, v116
	v_permlane32_swap_b32_e32 v109, v117
	v_cvt_pk_bf16_f32 v134, v122, v123
	v_cvt_pk_bf16_f32 v135, v124, v125
	v_cvt_pk_bf16_f32 v136, v130, v131
	v_cvt_pk_bf16_f32 v137, v132, v133
	v_add_u32_e32 v252, 0x0, v219
	global_store_dwordx4 v252, v[134:137], s[8:9]
	v_cvt_pk_bf16_f32 v118, v106, v107
	v_cvt_pk_bf16_f32 v119, v108, v109
	v_cvt_pk_bf16_f32 v120, v114, v115
	v_cvt_pk_bf16_f32 v121, v116, v117
	v_add_u32_e32 v253, 0xc000, v219
	global_store_dwordx4 v253, v[118:121], s[8:9]
	s_waitcnt vmcnt(18)
	v_permlane32_swap_b32_e32 v102, v98
	v_permlane32_swap_b32_e32 v103, v99
	v_permlane32_swap_b32_e32 v104, v100
	v_permlane32_swap_b32_e32 v105, v101
	v_permlane32_swap_b32_e32 v86, v82
	v_permlane32_swap_b32_e32 v87, v83
	v_permlane32_swap_b32_e32 v88, v84
	v_permlane32_swap_b32_e32 v89, v85
	v_pk_mul_f32 v[90:91], v[102:103], v[54:55]
	v_pk_mul_f32 v[92:93], v[104:105], v[56:57]
	v_pk_mul_f32 v[74:75], v[86:87], v[188:189]
	v_pk_mul_f32 v[76:77], v[88:89], v[190:191]
	v_pk_fma_f32 v[90:91], v[98:99], v[184:185], v[90:91] neg_lo:[1,0,0] neg_hi:[1,0,0]
	v_pk_fma_f32 v[92:93], v[100:101], v[186:187], v[92:93] neg_lo:[1,0,0] neg_hi:[1,0,0]
	v_pk_fma_f32 v[74:75], v[82:83], v[214:215], v[74:75] neg_lo:[1,0,0] neg_hi:[1,0,0]
	v_pk_fma_f32 v[76:77], v[84:85], v[216:217], v[76:77] neg_lo:[1,0,0] neg_hi:[1,0,0]
	v_pk_mul_f32 v[98:99], v[98:99], v[54:55]
	v_pk_mul_f32 v[100:101], v[100:101], v[56:57]
	v_pk_mul_f32 v[82:83], v[82:83], v[188:189]
	v_pk_mul_f32 v[84:85], v[84:85], v[190:191]
	v_pk_fma_f32 v[98:99], v[102:103], v[184:185], v[98:99]
	v_pk_fma_f32 v[100:101], v[104:105], v[186:187], v[100:101]
	v_pk_fma_f32 v[82:83], v[86:87], v[214:215], v[82:83]
	v_pk_fma_f32 v[84:85], v[88:89], v[216:217], v[84:85]
	v_permlane32_swap_b32_e32 v90, v98
	v_permlane32_swap_b32_e32 v91, v99
	v_permlane32_swap_b32_e32 v92, v100
	v_permlane32_swap_b32_e32 v93, v101
	v_permlane32_swap_b32_e32 v74, v82
	v_permlane32_swap_b32_e32 v75, v83
	v_permlane32_swap_b32_e32 v76, v84
	v_permlane32_swap_b32_e32 v77, v85
	v_cvt_pk_bf16_f32 v102, v90, v91
	v_cvt_pk_bf16_f32 v103, v92, v93
	v_cvt_pk_bf16_f32 v104, v98, v99
	v_cvt_pk_bf16_f32 v105, v100, v101
	v_add_u32_e32 v252, 0x18000, v219
	global_store_dwordx4 v252, v[102:105], s[8:9]
	v_cvt_pk_bf16_f32 v86, v74, v75
	v_cvt_pk_bf16_f32 v87, v76, v77
	v_cvt_pk_bf16_f32 v88, v82, v83
	v_cvt_pk_bf16_f32 v89, v84, v85
	v_add_u32_e32 v253, 0x24000, v219
	global_store_dwordx4 v253, v[86:89], s[8:9]
	s_waitcnt vmcnt(16)
	v_permlane32_swap_b32_e32 v70, v66
	v_permlane32_swap_b32_e32 v71, v67
	v_permlane32_swap_b32_e32 v72, v68
	v_permlane32_swap_b32_e32 v73, v69
	v_permlane32_swap_b32_e32 v46, v42
	v_permlane32_swap_b32_e32 v47, v43
	v_permlane32_swap_b32_e32 v48, v44
	v_permlane32_swap_b32_e32 v49, v45
	v_pk_mul_f32 v[58:59], v[70:71], v[150:151]
	v_pk_mul_f32 v[60:61], v[72:73], v[152:153]
	v_pk_mul_f32 v[34:35], v[46:47], v[158:159]
	v_pk_mul_f32 v[36:37], v[48:49], v[160:161]
	v_pk_fma_f32 v[58:59], v[66:67], v[154:155], v[58:59] neg_lo:[1,0,0] neg_hi:[1,0,0]
	v_pk_fma_f32 v[60:61], v[68:69], v[156:157], v[60:61] neg_lo:[1,0,0] neg_hi:[1,0,0]
	v_pk_fma_f32 v[34:35], v[42:43], v[162:163], v[34:35] neg_lo:[1,0,0] neg_hi:[1,0,0]
	v_pk_fma_f32 v[36:37], v[44:45], v[164:165], v[36:37] neg_lo:[1,0,0] neg_hi:[1,0,0]
	v_pk_mul_f32 v[66:67], v[66:67], v[150:151]
	v_pk_mul_f32 v[68:69], v[68:69], v[152:153]
	v_pk_mul_f32 v[42:43], v[42:43], v[158:159]
	v_pk_mul_f32 v[44:45], v[44:45], v[160:161]
	v_pk_fma_f32 v[66:67], v[70:71], v[154:155], v[66:67]
	v_pk_fma_f32 v[68:69], v[72:73], v[156:157], v[68:69]
	v_pk_fma_f32 v[42:43], v[46:47], v[162:163], v[42:43]
	v_pk_fma_f32 v[44:45], v[48:49], v[164:165], v[44:45]
	v_permlane32_swap_b32_e32 v58, v66
	v_permlane32_swap_b32_e32 v59, v67
	v_permlane32_swap_b32_e32 v60, v68
	v_permlane32_swap_b32_e32 v61, v69
	v_permlane32_swap_b32_e32 v34, v42
	v_permlane32_swap_b32_e32 v35, v43
	v_permlane32_swap_b32_e32 v36, v44
	v_permlane32_swap_b32_e32 v37, v45
	v_cvt_pk_bf16_f32 v70, v58, v59
	v_cvt_pk_bf16_f32 v71, v60, v61
	v_cvt_pk_bf16_f32 v72, v66, v67
	v_cvt_pk_bf16_f32 v73, v68, v69
	v_add_u32_e32 v252, 0x60000, v219
	global_store_dwordx4 v252, v[70:73], s[8:9]
	v_cvt_pk_bf16_f32 v46, v34, v35
	v_cvt_pk_bf16_f32 v47, v36, v37
	v_cvt_pk_bf16_f32 v48, v42, v43
	v_cvt_pk_bf16_f32 v49, v44, v45
	v_add_u32_e32 v253, 0x6c000, v219
	global_store_dwordx4 v253, v[46:49], s[8:9]
	s_waitcnt vmcnt(14)
	v_permlane32_swap_b32_e32 v30, v26
	v_permlane32_swap_b32_e32 v31, v27
	v_permlane32_swap_b32_e32 v32, v28
	v_permlane32_swap_b32_e32 v33, v29
	v_permlane32_swap_b32_e32 v14, v10
	v_permlane32_swap_b32_e32 v15, v11
	v_permlane32_swap_b32_e32 v16, v12
	v_permlane32_swap_b32_e32 v17, v13
	v_pk_mul_f32 v[18:19], v[30:31], v[166:167]
	v_pk_mul_f32 v[20:21], v[32:33], v[168:169]
	v_pk_mul_f32 v[2:3], v[14:15], v[174:175]
	v_pk_mul_f32 v[4:5], v[16:17], v[176:177]
	v_pk_fma_f32 v[18:19], v[26:27], v[170:171], v[18:19] neg_lo:[1,0,0] neg_hi:[1,0,0]
	v_pk_fma_f32 v[20:21], v[28:29], v[172:173], v[20:21] neg_lo:[1,0,0] neg_hi:[1,0,0]
	v_pk_fma_f32 v[2:3], v[10:11], v[180:181], v[2:3] neg_lo:[1,0,0] neg_hi:[1,0,0]
	v_pk_fma_f32 v[4:5], v[12:13], v[182:183], v[4:5] neg_lo:[1,0,0] neg_hi:[1,0,0]
	v_pk_mul_f32 v[26:27], v[26:27], v[166:167]
	v_pk_mul_f32 v[28:29], v[28:29], v[168:169]
	v_pk_mul_f32 v[10:11], v[10:11], v[174:175]
	v_pk_mul_f32 v[12:13], v[12:13], v[176:177]
	v_pk_fma_f32 v[26:27], v[30:31], v[170:171], v[26:27]
	v_pk_fma_f32 v[28:29], v[32:33], v[172:173], v[28:29]
	v_pk_fma_f32 v[10:11], v[14:15], v[180:181], v[10:11]
	v_pk_fma_f32 v[12:13], v[16:17], v[182:183], v[12:13]
	v_permlane32_swap_b32_e32 v18, v26
	v_permlane32_swap_b32_e32 v19, v27
	v_permlane32_swap_b32_e32 v20, v28
	v_permlane32_swap_b32_e32 v21, v29
	v_permlane32_swap_b32_e32 v2, v10
	v_permlane32_swap_b32_e32 v3, v11
	v_permlane32_swap_b32_e32 v4, v12
	v_permlane32_swap_b32_e32 v5, v13
	v_cvt_pk_bf16_f32 v30, v18, v19
	v_cvt_pk_bf16_f32 v31, v20, v21
	v_cvt_pk_bf16_f32 v32, v26, v27
	v_cvt_pk_bf16_f32 v33, v28, v29
	v_add_u32_e32 v252, 0x78000, v219
	global_store_dwordx4 v252, v[30:33], s[8:9]
	v_cvt_pk_bf16_f32 v14, v2, v3
	v_cvt_pk_bf16_f32 v15, v4, v5
	v_cvt_pk_bf16_f32 v16, v10, v11
	v_cvt_pk_bf16_f32 v17, v12, v13
	v_add_u32_e32 v253, 0x84000, v219
	global_store_dwordx4 v253, v[14:17], s[8:9]
	s_branch .Luq_end
.Luq_r1:
	v_and_b32_e32 v252, 1, v218
	v_and_b32_e32 v253, 2, v218
	v_lshlrev_b32_e32 v254, 6, v0
	v_lshl_add_u32 v254, v252, 5, v254
	v_lshl_add_u32 v254, v253, 3, v254
	v_add_u32_e32 v255, 0x2000, v254
	global_load_dwordx4 v[228:231], v254, s[10:11]
	global_load_dwordx4 v[232:235], v254, s[12:13]
	global_load_dwordx4 v[236:239], v254, s[10:11] offset:1024
	global_load_dwordx4 v[50:53], v254, s[12:13] offset:1024
	global_load_dwordx4 v[54:57], v254, s[10:11] offset:2048
	global_load_dwordx4 v[184:187], v254, s[12:13] offset:2048
	global_load_dwordx4 v[188:191], v254, s[10:11] offset:3072
	global_load_dwordx4 v[214:217], v254, s[12:13] offset:3072
	s_waitcnt vmcnt(8)
	v_add_f32_e32 v150, v151, v150
	v_add_f32_e32 v152, v152, v153
	v_add_f32_e32 v154, v155, v154
	v_add_f32_e32 v156, v156, v157
	v_add_f32_e32 v158, v159, v158
	v_add_f32_e32 v160, v160, v161
	v_add_f32_e32 v162, v163, v162
	v_add_f32_e32 v164, v164, v165
	v_add_f32_e32 v166, v167, v166
	v_add_f32_e32 v168, v168, v169
	v_add_f32_e32 v170, v171, v170
	v_add_f32_e32 v172, v172, v173
	v_add_f32_e32 v174, v175, v174
	v_add_f32_e32 v176, v176, v177
	v_add_f32_e32 v180, v181, v180
	v_add_f32_e32 v182, v182, v183
	v_add_f32_e32 v150, v150, v152
	v_add_f32_e32 v154, v154, v156
	v_add_f32_e32 v158, v158, v160
	v_add_f32_e32 v162, v162, v164
	v_add_f32_e32 v166, v166, v168
	v_add_f32_e32 v170, v170, v172
	v_add_f32_e32 v174, v174, v176
	v_add_f32_e32 v180, v180, v182
	v_cndmask_b32_e32 v150, 0, v150, vcc
	v_cndmask_b32_e32 v154, 0, v154, vcc
	v_cndmask_b32_e32 v158, 0, v158, vcc
	v_cndmask_b32_e32 v162, 0, v162, vcc
	v_cndmask_b32_e32 v166, 0, v166, vcc
	v_cndmask_b32_e32 v170, 0, v170, vcc
	v_cndmask_b32_e32 v174, 0, v174, vcc
	v_cndmask_b32_e32 v180, 0, v180, vcc
	ds_swizzle_b32 v151, v150 offset:swizzle(SWAP,16)
	ds_swizzle_b32 v155, v154 offset:swizzle(SWAP,16)
	ds_swizzle_b32 v159, v158 offset:swizzle(SWAP,16)
	ds_swizzle_b32 v163, v162 offset:swizzle(SWAP,16)
	ds_swizzle_b32 v167, v166 offset:swizzle(SWAP,16)
	ds_swizzle_b32 v171, v170 offset:swizzle(SWAP,16)
	ds_swizzle_b32 v175, v174 offset:swizzle(SWAP,16)
	ds_swizzle_b32 v181, v180 offset:swizzle(SWAP,16)
	s_waitcnt lgkmcnt(0)
	v_add_f32_e32 v150, v150, v151
	v_add_f32_e32 v154, v154, v155
	v_add_f32_e32 v158, v158, v159
	v_add_f32_e32 v162, v162, v163
	v_add_f32_e32 v166, v166, v167
	v_add_f32_e32 v170, v170, v171
	v_add_f32_e32 v174, v174, v175
	v_add_f32_e32 v180, v180, v181
	v_mov_b32_e32 v152, v150
	v_mov_b32_e32 v156, v154
	v_mov_b32_e32 v160, v158
	v_mov_b32_e32 v164, v162
	v_mov_b32_e32 v168, v166
	v_mov_b32_e32 v172, v170
	v_mov_b32_e32 v176, v174
	v_mov_b32_e32 v182, v180
	v_permlane32_swap_b32_e32 v150, v152
	v_permlane32_swap_b32_e32 v154, v156
	v_permlane32_swap_b32_e32 v158, v160
	v_permlane32_swap_b32_e32 v162, v164
	v_permlane32_swap_b32_e32 v166, v168
	v_permlane32_swap_b32_e32 v170, v172
	v_permlane32_swap_b32_e32 v174, v176
	v_permlane32_swap_b32_e32 v180, v182
	v_add_f32_e32 v150, v150, v152
	v_add_f32_e32 v154, v154, v156
	v_add_f32_e32 v158, v158, v160
	v_add_f32_e32 v162, v162, v164
	v_add_f32_e32 v166, v166, v168
	v_add_f32_e32 v170, v170, v172
	v_add_f32_e32 v174, v174, v176
	v_add_f32_e32 v180, v180, v182
	v_fmamk_f32 v150, v150, 0x3b2aaaab, v192
	v_fmamk_f32 v154, v154, 0x3b2aaaab, v192
	v_fmamk_f32 v158, v158, 0x3b2aaaab, v192
	v_fmamk_f32 v162, v162, 0x3b2aaaab, v192
	v_fmamk_f32 v166, v166, 0x3b2aaaab, v192
	v_fmamk_f32 v170, v170, 0x3b2aaaab, v192
	v_fmamk_f32 v174, v174, 0x3b2aaaab, v192
	v_fmamk_f32 v180, v180, 0x3b2aaaab, v192
	v_rsq_f32_e32 v150, v150
	v_rsq_f32_e32 v154, v154
	v_rsq_f32_e32 v158, v158
	v_rsq_f32_e32 v162, v162
	v_rsq_f32_e32 v166, v166
	v_rsq_f32_e32 v170, v170
	v_rsq_f32_e32 v174, v174
	v_rsq_f32_e32 v180, v180
	v_mul_f32_e32 v150, 0x3e16c740, v150
	v_mul_f32_e32 v154, 0x3e16c740, v154
	v_mul_f32_e32 v158, 0x3e16c740, v158
	v_mul_f32_e32 v162, 0x3e16c740, v162
	v_mul_f32_e32 v166, 0x3e16c740, v166
	v_mul_f32_e32 v170, 0x3e16c740, v170
	v_mul_f32_e32 v174, 0x3e16c740, v174
	v_mul_f32_e32 v180, 0x3e16c740, v180
	v_pk_mul_f32 v[134:135], v[134:135], v[150:151] op_sel_hi:[1,0]
	v_pk_mul_f32 v[136:137], v[136:137], v[150:151] op_sel_hi:[1,0]
	v_pk_mul_f32 v[130:131], v[130:131], v[150:151] op_sel_hi:[1,0]
	v_pk_mul_f32 v[132:133], v[132:133], v[150:151] op_sel_hi:[1,0]
	v_pk_mul_f32 v[126:127], v[126:127], v[150:151] op_sel_hi:[1,0]
	v_pk_mul_f32 v[128:129], v[128:129], v[150:151] op_sel_hi:[1,0]
	v_pk_mul_f32 v[122:123], v[122:123], v[150:151] op_sel_hi:[1,0]
	v_pk_mul_f32 v[124:125], v[124:125], v[150:151] op_sel_hi:[1,0]
	v_pk_mul_f32 v[118:119], v[118:119], v[154:155] op_sel_hi:[1,0]
	v_pk_mul_f32 v[120:121], v[120:121], v[154:155] op_sel_hi:[1,0]
	v_pk_mul_f32 v[114:115], v[114:115], v[154:155] op_sel_hi:[1,0]
	v_pk_mul_f32 v[116:117], v[116:117], v[154:155] op_sel_hi:[1,0]
	v_pk_mul_f32 v[110:111], v[110:111], v[154:155] op_sel_hi:[1,0]
	v_pk_mul_f32 v[112:113], v[112:113], v[154:155] op_sel_hi:[1,0]
	v_pk_mul_f32 v[106:107], v[106:107], v[154:155] op_sel_hi:[1,0]
	v_pk_mul_f32 v[108:109], v[108:109], v[154:155] op_sel_hi:[1,0]
	v_pk_mul_f32 v[102:103], v[102:103], v[158:159] op_sel_hi:[1,0]
	v_pk_mul_f32 v[104:105], v[104:105], v[158:159] op_sel_hi:[1,0]
	v_pk_mul_f32 v[98:99], v[98:99], v[158:159] op_sel_hi:[1,0]
	v_pk_mul_f32 v[100:101], v[100:101], v[158:159] op_sel_hi:[1,0]
	v_pk_mul_f32 v[94:95], v[94:95], v[158:159] op_sel_hi:[1,0]
	v_pk_mul_f32 v[96:97], v[96:97], v[158:159] op_sel_hi:[1,0]
	v_pk_mul_f32 v[90:91], v[90:91], v[158:159] op_sel_hi:[1,0]
	v_pk_mul_f32 v[92:93], v[92:93], v[158:159] op_sel_hi:[1,0]
	v_pk_mul_f32 v[86:87], v[86:87], v[162:163] op_sel_hi:[1,0]
	v_pk_mul_f32 v[88:89], v[88:89], v[162:163] op_sel_hi:[1,0]
	v_pk_mul_f32 v[82:83], v[82:83], v[162:163] op_sel_hi:[1,0]
	v_pk_mul_f32 v[84:85], v[84:85], v[162:163] op_sel_hi:[1,0]
	v_pk_mul_f32 v[78:79], v[78:79], v[162:163] op_sel_hi:[1,0]
	v_pk_mul_f32 v[80:81], v[80:81], v[162:163] op_sel_hi:[1,0]
	v_pk_mul_f32 v[74:75], v[74:75], v[162:163] op_sel_hi:[1,0]
	v_pk_mul_f32 v[76:77], v[76:77], v[162:163] op_sel_hi:[1,0]
	v_pk_mul_f32 v[70:71], v[70:71], v[166:167] op_sel_hi:[1,0]
	v_pk_mul_f32 v[72:73], v[72:73], v[166:167] op_sel_hi:[1,0]
	v_pk_mul_f32 v[66:67], v[66:67], v[166:167] op_sel_hi:[1,0]
	v_pk_mul_f32 v[68:69], v[68:69], v[166:167] op_sel_hi:[1,0]
	v_pk_mul_f32 v[62:63], v[62:63], v[166:167] op_sel_hi:[1,0]
	v_pk_mul_f32 v[64:65], v[64:65], v[166:167] op_sel_hi:[1,0]
	v_pk_mul_f32 v[58:59], v[58:59], v[166:167] op_sel_hi:[1,0]
	v_pk_mul_f32 v[60:61], v[60:61], v[166:167] op_sel_hi:[1,0]
	v_pk_mul_f32 v[46:47], v[46:47], v[170:171] op_sel_hi:[1,0]
	v_pk_mul_f32 v[48:49], v[48:49], v[170:171] op_sel_hi:[1,0]
	v_pk_mul_f32 v[42:43], v[42:43], v[170:171] op_sel_hi:[1,0]
	v_pk_mul_f32 v[44:45], v[44:45], v[170:171] op_sel_hi:[1,0]
	v_pk_mul_f32 v[38:39], v[38:39], v[170:171] op_sel_hi:[1,0]
	v_pk_mul_f32 v[40:41], v[40:41], v[170:171] op_sel_hi:[1,0]
	v_pk_mul_f32 v[34:35], v[34:35], v[170:171] op_sel_hi:[1,0]
	v_pk_mul_f32 v[36:37], v[36:37], v[170:171] op_sel_hi:[1,0]
	v_pk_mul_f32 v[30:31], v[30:31], v[174:175] op_sel_hi:[1,0]
	v_pk_mul_f32 v[32:33], v[32:33], v[174:175] op_sel_hi:[1,0]
	v_pk_mul_f32 v[26:27], v[26:27], v[174:175] op_sel_hi:[1,0]
	v_pk_mul_f32 v[28:29], v[28:29], v[174:175] op_sel_hi:[1,0]
	v_pk_mul_f32 v[22:23], v[22:23], v[174:175] op_sel_hi:[1,0]
	v_pk_mul_f32 v[24:25], v[24:25], v[174:175] op_sel_hi:[1,0]
	v_pk_mul_f32 v[18:19], v[18:19], v[174:175] op_sel_hi:[1,0]
	v_pk_mul_f32 v[20:21], v[20:21], v[174:175] op_sel_hi:[1,0]
	v_pk_mul_f32 v[14:15], v[14:15], v[180:181] op_sel_hi:[1,0]
	v_pk_mul_f32 v[16:17], v[16:17], v[180:181] op_sel_hi:[1,0]
	v_pk_mul_f32 v[10:11], v[10:11], v[180:181] op_sel_hi:[1,0]
	v_pk_mul_f32 v[12:13], v[12:13], v[180:181] op_sel_hi:[1,0]
	v_pk_mul_f32 v[6:7], v[6:7], v[180:181] op_sel_hi:[1,0]
	v_pk_mul_f32 v[8:9], v[8:9], v[180:181] op_sel_hi:[1,0]
	v_pk_mul_f32 v[2:3], v[2:3], v[180:181] op_sel_hi:[1,0]
	v_pk_mul_f32 v[4:5], v[4:5], v[180:181] op_sel_hi:[1,0]
	global_load_dwordx4 v[150:153], v255, s[10:11]
	global_load_dwordx4 v[154:157], v255, s[12:13]
	global_load_dwordx4 v[158:161], v255, s[10:11] offset:1024
	global_load_dwordx4 v[162:165], v255, s[12:13] offset:1024
	global_load_dwordx4 v[166:169], v255, s[10:11] offset:2048
	global_load_dwordx4 v[170:173], v255, s[12:13] offset:2048
	global_load_dwordx4 v[174:177], v255, s[10:11] offset:3072
	global_load_dwordx4 v[180:183], v255, s[12:13] offset:3072
	v_cvt_pk_bf16_f32 v134, v134, v135
	v_cvt_pk_bf16_f32 v135, v136, v137
	v_cvt_pk_bf16_f32 v136, v130, v131
	v_cvt_pk_bf16_f32 v137, v132, v133
	v_add_u32_e32 v252, 0x0, v219
	global_store_dwordx4 v252, v[134:137], s[8:9]
	v_cvt_pk_bf16_f32 v118, v118, v119
	v_cvt_pk_bf16_f32 v119, v120, v121
	v_cvt_pk_bf16_f32 v120, v114, v115
	v_cvt_pk_bf16_f32 v121, v116, v117
	v_add_u32_e32 v253, 0xc000, v219
	global_store_dwordx4 v253, v[118:121], s[8:9]
	v_cvt_pk_bf16_f32 v102, v102, v103
	v_cvt_pk_bf16_f32 v103, v104, v105
	v_cvt_pk_bf16_f32 v104, v98, v99
	v_cvt_pk_bf16_f32 v105, v100, v101
	v_add_u32_e32 v252, 0x18000, v219
	global_store_dwordx4 v252, v[102:105], s[8:9]
	v_cvt_pk_bf16_f32 v86, v86, v87
	v_cvt_pk_bf16_f32 v87, v88, v89
	v_cvt_pk_bf16_f32 v88, v82, v83
	v_cvt_pk_bf16_f32 v89, v84, v85
	v_add_u32_e32 v253, 0x24000, v219
	global_store_dwordx4 v253, v[86:89], s[8:9]
	v_cvt_pk_bf16_f32 v70, v70, v71
	v_cvt_pk_bf16_f32 v71, v72, v73
	v_cvt_pk_bf16_f32 v72, v66, v67
	v_cvt_pk_bf16_f32 v73, v68, v69
	v_add_u32_e32 v252, 0x60000, v219
	global_store_dwordx4 v252, v[70:73], s[8:9]
	v_cvt_pk_bf16_f32 v46, v46, v47
	v_cvt_pk_bf16_f32 v47, v48, v49
	v_cvt_pk_bf16_f32 v48, v42, v43
	v_cvt_pk_bf16_f32 v49, v44, v45
	v_add_u32_e32 v253, 0x6c000, v219
	global_store_dwordx4 v253, v[46:49], s[8:9]
	v_cvt_pk_bf16_f32 v30, v30, v31
	v_cvt_pk_bf16_f32 v31, v32, v33
	v_cvt_pk_bf16_f32 v32, v26, v27
	v_cvt_pk_bf16_f32 v33, v28, v29
	v_add_u32_e32 v252, 0x78000, v219
	global_store_dwordx4 v252, v[30:33], s[8:9]
	v_cvt_pk_bf16_f32 v14, v14, v15
	v_cvt_pk_bf16_f32 v15, v16, v17
	v_cvt_pk_bf16_f32 v16, v10, v11
	v_cvt_pk_bf16_f32 v17, v12, v13
	v_add_u32_e32 v253, 0x84000, v219
	global_store_dwordx4 v253, v[14:17], s[8:9]
	s_waitcnt vmcnt(20)
	v_permlane32_swap_b32_e32 v126, v122
	v_permlane32_swap_b32_e32 v127, v123
	v_permlane32_swap_b32_e32 v128, v124
	v_permlane32_swap_b32_e32 v129, v125
	v_permlane32_swap_b32_e32 v110, v106
	v_permlane32_swap_b32_e32 v111, v107
	v_permlane32_swap_b32_e32 v112, v108
	v_permlane32_swap_b32_e32 v113, v109
	v_pk_mul_f32 v[130:131], v[126:127], v[228:229]
	v_pk_mul_f32 v[132:133], v[128:129], v[230:231]
	v_pk_mul_f32 v[114:115], v[110:111], v[236:237]
	v_pk_mul_f32 v[116:117], v[112:113], v[238:239]
	v_pk_fma_f32 v[130:131], v[122:123], v[232:233], v[130:131] neg_lo:[1,0,0] neg_hi:[1,0,0]
	v_pk_fma_f32 v[132:133], v[124:125], v[234:235], v[132:133] neg_lo:[1,0,0] neg_hi:[1,0,0]
	v_pk_fma_f32 v[114:115], v[106:107], v[50:51], v[114:115] neg_lo:[1,0,0] neg_hi:[1,0,0]
	v_pk_fma_f32 v[116:117], v[108:109], v[52:53], v[116:117] neg_lo:[1,0,0] neg_hi:[1,0,0]
	v_pk_mul_f32 v[122:123], v[122:123], v[228:229]
	v_pk_mul_f32 v[124:125], v[124:125], v[230:231]
	v_pk_mul_f32 v[106:107], v[106:107], v[236:237]
	v_pk_mul_f32 v[108:109], v[108:109], v[238:239]
	v_pk_fma_f32 v[122:123], v[126:127], v[232:233], v[122:123]
	v_pk_fma_f32 v[124:125], v[128:129], v[234:235], v[124:125]
	v_pk_fma_f32 v[106:107], v[110:111], v[50:51], v[106:107]
	v_pk_fma_f32 v[108:109], v[112:113], v[52:53], v[108:109]
	v_permlane32_swap_b32_e32 v130, v122
	v_permlane32_swap_b32_e32 v131, v123
	v_permlane32_swap_b32_e32 v132, v124
	v_permlane32_swap_b32_e32 v133, v125
	v_permlane32_swap_b32_e32 v114, v106
	v_permlane32_swap_b32_e32 v115, v107
	v_permlane32_swap_b32_e32 v116, v108
	v_permlane32_swap_b32_e32 v117, v109
	v_cvt_pk_bf16_f32 v126, v130, v131
	v_cvt_pk_bf16_f32 v127, v132, v133
	v_cvt_pk_bf16_f32 v128, v122, v123
	v_cvt_pk_bf16_f32 v129, v124, v125
	v_add_u32_e32 v252, 0x0, v219
	global_store_dwordx4 v252, v[126:129], s[8:9] offset:256
	v_cvt_pk_bf16_f32 v110, v114, v115
	v_cvt_pk_bf16_f32 v111, v116, v117
	v_cvt_pk_bf16_f32 v112, v106, v107
	v_cvt_pk_bf16_f32 v113, v108, v109
	v_add_u32_e32 v253, 0xc000, v219
	global_store_dwordx4 v253, v[110:113], s[8:9] offset:256
	s_waitcnt vmcnt(18)
	v_permlane32_swap_b32_e32 v94, v90
	v_permlane32_swap_b32_e32 v95, v91
	v_permlane32_swap_b32_e32 v96, v92
	v_permlane32_swap_b32_e32 v97, v93
	v_permlane32_swap_b32_e32 v78, v74
	v_permlane32_swap_b32_e32 v79, v75
	v_permlane32_swap_b32_e32 v80, v76
	v_permlane32_swap_b32_e32 v81, v77
	v_pk_mul_f32 v[98:99], v[94:95], v[54:55]
	v_pk_mul_f32 v[100:101], v[96:97], v[56:57]
	v_pk_mul_f32 v[82:83], v[78:79], v[188:189]
	v_pk_mul_f32 v[84:85], v[80:81], v[190:191]
	v_pk_fma_f32 v[98:99], v[90:91], v[184:185], v[98:99] neg_lo:[1,0,0] neg_hi:[1,0,0]
	v_pk_fma_f32 v[100:101], v[92:93], v[186:187], v[100:101] neg_lo:[1,0,0] neg_hi:[1,0,0]
	v_pk_fma_f32 v[82:83], v[74:75], v[214:215], v[82:83] neg_lo:[1,0,0] neg_hi:[1,0,0]
	v_pk_fma_f32 v[84:85], v[76:77], v[216:217], v[84:85] neg_lo:[1,0,0] neg_hi:[1,0,0]
	v_pk_mul_f32 v[90:91], v[90:91], v[54:55]
	v_pk_mul_f32 v[92:93], v[92:93], v[56:57]
	v_pk_mul_f32 v[74:75], v[74:75], v[188:189]
	v_pk_mul_f32 v[76:77], v[76:77], v[190:191]
	v_pk_fma_f32 v[90:91], v[94:95], v[184:185], v[90:91]
	v_pk_fma_f32 v[92:93], v[96:97], v[186:187], v[92:93]
	v_pk_fma_f32 v[74:75], v[78:79], v[214:215], v[74:75]
	v_pk_fma_f32 v[76:77], v[80:81], v[216:217], v[76:77]
	v_permlane32_swap_b32_e32 v98, v90
	v_permlane32_swap_b32_e32 v99, v91
	v_permlane32_swap_b32_e32 v100, v92
	v_permlane32_swap_b32_e32 v101, v93
	v_permlane32_swap_b32_e32 v82, v74
	v_permlane32_swap_b32_e32 v83, v75
	v_permlane32_swap_b32_e32 v84, v76
	v_permlane32_swap_b32_e32 v85, v77
	v_cvt_pk_bf16_f32 v94, v98, v99
	v_cvt_pk_bf16_f32 v95, v100, v101
	v_cvt_pk_bf16_f32 v96, v90, v91
	v_cvt_pk_bf16_f32 v97, v92, v93
	v_add_u32_e32 v252, 0x18000, v219
	global_store_dwordx4 v252, v[94:97], s[8:9] offset:256
	v_cvt_pk_bf16_f32 v78, v82, v83
	v_cvt_pk_bf16_f32 v79, v84, v85
	v_cvt_pk_bf16_f32 v80, v74, v75
	v_cvt_pk_bf16_f32 v81, v76, v77
	v_add_u32_e32 v253, 0x24000, v219
	global_store_dwordx4 v253, v[78:81], s[8:9] offset:256
	s_waitcnt vmcnt(16)
	v_permlane32_swap_b32_e32 v62, v58
	v_permlane32_swap_b32_e32 v63, v59
	v_permlane32_swap_b32_e32 v64, v60
	v_permlane32_swap_b32_e32 v65, v61
	v_permlane32_swap_b32_e32 v38, v34
	v_permlane32_swap_b32_e32 v39, v35
	v_permlane32_swap_b32_e32 v40, v36
	v_permlane32_swap_b32_e32 v41, v37
	v_pk_mul_f32 v[66:67], v[62:63], v[150:151]
	v_pk_mul_f32 v[68:69], v[64:65], v[152:153]
	v_pk_mul_f32 v[42:43], v[38:39], v[158:159]
	v_pk_mul_f32 v[44:45], v[40:41], v[160:161]
	v_pk_fma_f32 v[66:67], v[58:59], v[154:155], v[66:67] neg_lo:[1,0,0] neg_hi:[1,0,0]
	v_pk_fma_f32 v[68:69], v[60:61], v[156:157], v[68:69] neg_lo:[1,0,0] neg_hi:[1,0,0]
	v_pk_fma_f32 v[42:43], v[34:35], v[162:163], v[42:43] neg_lo:[1,0,0] neg_hi:[1,0,0]
	v_pk_fma_f32 v[44:45], v[36:37], v[164:165], v[44:45] neg_lo:[1,0,0] neg_hi:[1,0,0]
	v_pk_mul_f32 v[58:59], v[58:59], v[150:151]
	v_pk_mul_f32 v[60:61], v[60:61], v[152:153]
	v_pk_mul_f32 v[34:35], v[34:35], v[158:159]
	v_pk_mul_f32 v[36:37], v[36:37], v[160:161]
	v_pk_fma_f32 v[58:59], v[62:63], v[154:155], v[58:59]
	v_pk_fma_f32 v[60:61], v[64:65], v[156:157], v[60:61]
	v_pk_fma_f32 v[34:35], v[38:39], v[162:163], v[34:35]
	v_pk_fma_f32 v[36:37], v[40:41], v[164:165], v[36:37]
	v_permlane32_swap_b32_e32 v66, v58
	v_permlane32_swap_b32_e32 v67, v59
	v_permlane32_swap_b32_e32 v68, v60
	v_permlane32_swap_b32_e32 v69, v61
	v_permlane32_swap_b32_e32 v42, v34
	v_permlane32_swap_b32_e32 v43, v35
	v_permlane32_swap_b32_e32 v44, v36
	v_permlane32_swap_b32_e32 v45, v37
	v_cvt_pk_bf16_f32 v62, v66, v67
	v_cvt_pk_bf16_f32 v63, v68, v69
	v_cvt_pk_bf16_f32 v64, v58, v59
	v_cvt_pk_bf16_f32 v65, v60, v61
	v_add_u32_e32 v252, 0x60000, v219
	global_store_dwordx4 v252, v[62:65], s[8:9] offset:256
	v_cvt_pk_bf16_f32 v38, v42, v43
	v_cvt_pk_bf16_f32 v39, v44, v45
	v_cvt_pk_bf16_f32 v40, v34, v35
	v_cvt_pk_bf16_f32 v41, v36, v37
	v_add_u32_e32 v253, 0x6c000, v219
	global_store_dwordx4 v253, v[38:41], s[8:9] offset:256
	s_waitcnt vmcnt(14)
	v_permlane32_swap_b32_e32 v22, v18
	v_permlane32_swap_b32_e32 v23, v19
	v_permlane32_swap_b32_e32 v24, v20
	v_permlane32_swap_b32_e32 v25, v21
	v_permlane32_swap_b32_e32 v6, v2
	v_permlane32_swap_b32_e32 v7, v3
	v_permlane32_swap_b32_e32 v8, v4
	v_permlane32_swap_b32_e32 v9, v5
	v_pk_mul_f32 v[26:27], v[22:23], v[166:167]
	v_pk_mul_f32 v[28:29], v[24:25], v[168:169]
	v_pk_mul_f32 v[10:11], v[6:7], v[174:175]
	v_pk_mul_f32 v[12:13], v[8:9], v[176:177]
	v_pk_fma_f32 v[26:27], v[18:19], v[170:171], v[26:27] neg_lo:[1,0,0] neg_hi:[1,0,0]
	v_pk_fma_f32 v[28:29], v[20:21], v[172:173], v[28:29] neg_lo:[1,0,0] neg_hi:[1,0,0]
	v_pk_fma_f32 v[10:11], v[2:3], v[180:181], v[10:11] neg_lo:[1,0,0] neg_hi:[1,0,0]
	v_pk_fma_f32 v[12:13], v[4:5], v[182:183], v[12:13] neg_lo:[1,0,0] neg_hi:[1,0,0]
	v_pk_mul_f32 v[18:19], v[18:19], v[166:167]
	v_pk_mul_f32 v[20:21], v[20:21], v[168:169]
	v_pk_mul_f32 v[2:3], v[2:3], v[174:175]
	v_pk_mul_f32 v[4:5], v[4:5], v[176:177]
	v_pk_fma_f32 v[18:19], v[22:23], v[170:171], v[18:19]
	v_pk_fma_f32 v[20:21], v[24:25], v[172:173], v[20:21]
	v_pk_fma_f32 v[2:3], v[6:7], v[180:181], v[2:3]
	v_pk_fma_f32 v[4:5], v[8:9], v[182:183], v[4:5]
	v_permlane32_swap_b32_e32 v26, v18
	v_permlane32_swap_b32_e32 v27, v19
	v_permlane32_swap_b32_e32 v28, v20
	v_permlane32_swap_b32_e32 v29, v21
	v_permlane32_swap_b32_e32 v10, v2
	v_permlane32_swap_b32_e32 v11, v3
	v_permlane32_swap_b32_e32 v12, v4
	v_permlane32_swap_b32_e32 v13, v5
	v_cvt_pk_bf16_f32 v22, v26, v27
	v_cvt_pk_bf16_f32 v23, v28, v29
	v_cvt_pk_bf16_f32 v24, v18, v19
	v_cvt_pk_bf16_f32 v25, v20, v21
	v_add_u32_e32 v252, 0x78000, v219
	global_store_dwordx4 v252, v[22:25], s[8:9] offset:256
	v_cvt_pk_bf16_f32 v6, v10, v11
	v_cvt_pk_bf16_f32 v7, v12, v13
	v_cvt_pk_bf16_f32 v8, v2, v3
	v_cvt_pk_bf16_f32 v9, v4, v5
	v_add_u32_e32 v253, 0x84000, v219
	global_store_dwordx4 v253, v[6:9], s[8:9] offset:256
.Luq_end:
	s_and_b64 vcc, exec, s[36:37]
	s_mov_b64 s[2:3], -1
	s_cbranch_vccnz .LBB0_260
	s_andn2_b64 vcc, exec, s[6:7]
	s_cbranch_vccnz .LBB0_259
	s_barrier
	s_branch .LBB0_259
